# cache-policy: nt hint also removed from the P0 weight / x loads (no nt loads left)
# baseline (speedup 1.0000x reference)
; #define LAS __attribute__((address_space(3)))
; #define LDS_WAIT() asm volatile("s_waitcnt lgkmcnt(0)" ::: "memory")
; __device__ __forceinline__ unsigned pk2(float lo, float hi) { return pg8::cvt_pk_bf16(lo, hi); }
; __device__ __forceinline__ void p0_transpose_item(const float* W, int K, int N, bfu* WT, int drow0, LAS float* scr, int k0, int n0, int lane, const float* gk) {
; #pragma unroll 8
;     for (int i = 0; i < 32; ++i) { const int kk = 2 * i + (lane >> 5); scr[kk * 33 + (lane & 31)] = __builtin_nontemporal_load(W + (size_t)(k0 + kk) * N + n0 + (lane & 31)); }
;     LDS_WAIT(); asm volatile("" ::: "memory");
;     const int c = lane & 7;
;     f32x4 ga = (f32x4){1.f, 1.f, 1.f, 1.f}, gb = ga;
;     if (gk) { ga = *(const f32x4*)(gk + k0 + 8 * c); gb = *(const f32x4*)(gk + k0 + 8 * c + 4); }
; #pragma unroll
;     for (int j = 0; j < 4; ++j) { const int n = (lane >> 3) + 8 * j; const LAS float* s = scr + (8 * c) * 33 + n;
;         v4u o; o.x = pk2(s[0 * 33] * ga.x, s[1 * 33] * ga.y); o.y = pk2(s[2 * 33] * ga.z, s[3 * 33] * ga.w); o.z = pk2(s[4 * 33] * gb.x, s[5 * 33] * gb.y); o.w = pk2(s[6 * 33] * gb.z, s[7 * 33] * gb.w);
;         *(v4u*)(WT + (size_t)(drow0 + n) * K + k0 + 8 * c) = o; }
;     LDS_WAIT(); asm volatile("" ::: "memory");
; }
.LBB0_28:
	v_lshl_add_u64 v[54:55], v[20:21], 0, s[26:27]
	v_lshl_add_u64 v[56:57], v[18:19], 0, s[26:27]
	v_lshl_add_u64 v[58:59], v[16:17], 0, s[26:27]
	v_lshl_add_u64 v[60:61], v[14:15], 0, s[26:27]
	v_lshl_add_u64 v[62:63], v[6:7], 0, s[26:27]
	v_lshl_add_u64 v[64:65], v[4:5], 0, s[26:27]
	v_lshl_add_u64 v[66:67], v[2:3], 0, s[26:27]
	v_lshl_add_u64 v[68:69], v[0:1], 0, s[26:27]
	global_load_dword v70, v[54:55], off
	global_load_dword v71, v[56:57], off
	global_load_dword v72, v[58:59], off
	global_load_dword v73, v[60:61], off
	global_load_dword v74, v[62:63], off
	global_load_dword v75, v[64:65], off
	global_load_dword v76, v[66:67], off
	global_load_dword v77, v[68:69], off
	s_add_u32 s26, s26, 0x20000
	s_addc_u32 s27, s27, 0
	v_lshl_add_u64 v[54:55], v[20:21], 0, s[26:27]
	v_lshl_add_u64 v[56:57], v[18:19], 0, s[26:27]
	v_lshl_add_u64 v[58:59], v[16:17], 0, s[26:27]
	v_lshl_add_u64 v[60:61], v[14:15], 0, s[26:27]
	v_lshl_add_u64 v[62:63], v[6:7], 0, s[26:27]
	v_lshl_add_u64 v[64:65], v[4:5], 0, s[26:27]
	v_lshl_add_u64 v[66:67], v[2:3], 0, s[26:27]
	v_lshl_add_u64 v[68:69], v[0:1], 0, s[26:27]
	global_load_dword v78, v[54:55], off
	global_load_dword v79, v[56:57], off
	global_load_dword v80, v[58:59], off
	global_load_dword v81, v[60:61], off
	global_load_dword v82, v[62:63], off
	global_load_dword v83, v[64:65], off
	global_load_dword v84, v[66:67], off
	global_load_dword v85, v[68:69], off
	s_add_u32 s26, s26, 0x20000
	s_addc_u32 s27, s27, 0
	v_lshl_add_u64 v[54:55], v[20:21], 0, s[26:27]
	v_lshl_add_u64 v[56:57], v[18:19], 0, s[26:27]
	v_lshl_add_u64 v[58:59], v[16:17], 0, s[26:27]
	v_lshl_add_u64 v[60:61], v[14:15], 0, s[26:27]
	v_lshl_add_u64 v[62:63], v[6:7], 0, s[26:27]
	v_lshl_add_u64 v[64:65], v[4:5], 0, s[26:27]
	v_lshl_add_u64 v[66:67], v[2:3], 0, s[26:27]
	v_lshl_add_u64 v[68:69], v[0:1], 0, s[26:27]
	global_load_dword v86, v[54:55], off
	global_load_dword v87, v[56:57], off
	global_load_dword v88, v[58:59], off
	global_load_dword v89, v[60:61], off
	global_load_dword v90, v[62:63], off
	global_load_dword v91, v[64:65], off
	global_load_dword v92, v[66:67], off
	global_load_dword v93, v[68:69], off
	s_add_u32 s26, s26, 0x20000
	s_addc_u32 s27, s27, 0
	v_lshl_add_u64 v[54:55], v[20:21], 0, s[26:27]
	v_lshl_add_u64 v[56:57], v[18:19], 0, s[26:27]
	v_lshl_add_u64 v[58:59], v[16:17], 0, s[26:27]
	v_lshl_add_u64 v[60:61], v[14:15], 0, s[26:27]
	v_lshl_add_u64 v[62:63], v[6:7], 0, s[26:27]
	v_lshl_add_u64 v[64:65], v[4:5], 0, s[26:27]
	v_lshl_add_u64 v[66:67], v[2:3], 0, s[26:27]
	v_lshl_add_u64 v[68:69], v[0:1], 0, s[26:27]
	global_load_dword v94, v[54:55], off
	global_load_dword v95, v[56:57], off
	global_load_dword v96, v[58:59], off
	global_load_dword v97, v[60:61], off
	global_load_dword v98, v[62:63], off
	global_load_dword v99, v[64:65], off
	global_load_dword v100, v[66:67], off
	global_load_dword v101, v[68:69], off
	s_add_u32 s26, s26, 0x20000
	s_addc_u32 s27, s27, 0
	v_add_u32_e32 v54, 0x400, v10
	s_waitcnt vmcnt(30)
	ds_write2_b32 v10, v70, v71 offset1:66
	s_waitcnt vmcnt(28)
	ds_write2_b32 v10, v72, v73 offset0:132 offset1:198
	s_waitcnt vmcnt(26)
	ds_write2_b32 v54, v74, v75 offset0:8 offset1:74
	s_waitcnt vmcnt(24)
	ds_write2_b32 v54, v76, v77 offset0:140 offset1:206
	v_add_u32_e32 v10, 0x840, v10
	v_add_u32_e32 v54, 0x400, v10
	s_waitcnt vmcnt(22)
	ds_write2_b32 v10, v78, v79 offset1:66
	s_waitcnt vmcnt(20)
	ds_write2_b32 v10, v80, v81 offset0:132 offset1:198
	s_waitcnt vmcnt(18)
	ds_write2_b32 v54, v82, v83 offset0:8 offset1:74
	s_waitcnt vmcnt(16)
	ds_write2_b32 v54, v84, v85 offset0:140 offset1:206
	v_add_u32_e32 v10, 0x840, v10
	v_add_u32_e32 v54, 0x400, v10
	s_waitcnt vmcnt(14)
	ds_write2_b32 v10, v86, v87 offset1:66
	s_waitcnt vmcnt(12)
	ds_write2_b32 v10, v88, v89 offset0:132 offset1:198
	s_waitcnt vmcnt(10)
	ds_write2_b32 v54, v90, v91 offset0:8 offset1:74
	s_waitcnt vmcnt(8)
	ds_write2_b32 v54, v92, v93 offset0:140 offset1:206
	v_add_u32_e32 v10, 0x840, v10
	v_add_u32_e32 v54, 0x400, v10
	s_waitcnt vmcnt(6)
	ds_write2_b32 v10, v94, v95 offset1:66
	s_waitcnt vmcnt(4)
	ds_write2_b32 v10, v96, v97 offset0:132 offset1:198
	s_waitcnt vmcnt(2)
	ds_write2_b32 v54, v98, v99 offset0:8 offset1:74
	s_waitcnt vmcnt(0)
	ds_write2_b32 v54, v100, v101 offset0:140 offset1:206
	v_add_u32_e32 v10, 0x840, v10
	s_and_b32 s4, s30, 0x7fffffc0
	s_lshl_b32 s27, s38, 5
	s_addk_i32 s4, 0xb300
	s_mul_i32 s26, s22, 0x1600000
	s_and_b32 s27, s27, 0x7e0
	s_mul_hi_i32 s23, s22, 0x1600000
	s_add_u32 s26, s24, s26
	s_addc_u32 s23, s25, s23
	s_waitcnt lgkmcnt(0)
	s_lshl_b64 s[24:25], s[4:5], 1
	s_add_u32 s24, s26, s24
	s_addc_u32 s25, s23, s25
	v_lshlrev_b32_e32 v10, 1, v8
	ds_read2_b32 v[4:5], v25 offset0:33 offset1:41
	ds_read2_b32 v[6:7], v25 offset1:8
	ds_read2_b32 v[14:15], v25 offset0:66 offset1:74
	ds_read2_b32 v[16:17], v25 offset0:99 offset1:107
	ds_read2_b32 v[18:19], v25 offset0:132 offset1:140
	ds_read2_b32 v[20:21], v25 offset0:165 offset1:173
	ds_read2_b32 v[54:55], v25 offset0:198 offset1:206
	ds_read2_b32 v[56:57], v25 offset0:231 offset1:239
	v_lshl_add_u64 v[0:1], s[24:25], 0, v[10:11]
	v_lshl_add_u64 v[58:59], v[0:1], 0, s[6:7]
	s_waitcnt lgkmcnt(6)
	v_cvt_pk_bf16_f32 v0, v6, v4
	v_or_b32_e32 v4, s27, v24
	v_mul_u32_u24_e32 v4, 0x1600, v4
	v_lshlrev_b32_e32 v10, 1, v4
	s_waitcnt lgkmcnt(4)
	v_cvt_pk_bf16_f32 v1, v14, v16
	s_waitcnt lgkmcnt(2)
	v_cvt_pk_bf16_f32 v2, v18, v20
	s_waitcnt lgkmcnt(0)
	v_cvt_pk_bf16_f32 v3, v54, v56
	v_lshl_add_u64 v[60:61], v[58:59], 0, v[10:11]
	v_or_b32_e32 v4, s27, v26
	global_store_dwordx4 v[60:61], v[0:3], off
	v_mul_u32_u24_e32 v4, 0x1600, v4
	v_lshlrev_b32_e32 v10, 1, v4
	v_cvt_pk_bf16_f32 v0, v7, v5
	v_cvt_pk_bf16_f32 v1, v15, v17
	v_cvt_pk_bf16_f32 v2, v19, v21
	v_cvt_pk_bf16_f32 v3, v55, v57
	ds_read2_b32 v[6:7], v25 offset0:16 offset1:24
	ds_read2_b32 v[14:15], v25 offset0:49 offset1:57
	ds_read2_b32 v[16:17], v25 offset0:82 offset1:90
	ds_read2_b32 v[18:19], v25 offset0:115 offset1:123
	ds_read2_b32 v[20:21], v25 offset0:148 offset1:156
	ds_read2_b32 v[54:55], v25 offset0:181 offset1:189
	ds_read2_b32 v[56:57], v25 offset0:214 offset1:222
	ds_read2_b32 v[60:61], v25 offset0:247 offset1:255
	v_lshl_add_u64 v[4:5], v[58:59], 0, v[10:11]
	global_store_dwordx4 v[4:5], v[0:3], off
	v_or_b32_e32 v4, s27, v27
	v_mul_u32_u24_e32 v4, 0x1600, v4
	v_lshlrev_b32_e32 v10, 1, v4
	s_waitcnt lgkmcnt(6)
	v_cvt_pk_bf16_f32 v0, v6, v14
	s_waitcnt lgkmcnt(4)
	v_cvt_pk_bf16_f32 v1, v16, v18
	s_waitcnt lgkmcnt(2)
	v_cvt_pk_bf16_f32 v2, v20, v54
	s_waitcnt lgkmcnt(0)
	v_cvt_pk_bf16_f32 v3, v56, v60
	v_lshl_add_u64 v[4:5], v[58:59], 0, v[10:11]
	global_store_dwordx4 v[4:5], v[0:3], off
	v_or_b32_e32 v4, s27, v28
	v_mul_u32_u24_e32 v4, 0x1600, v4
	v_lshlrev_b32_e32 v10, 1, v4
	v_cvt_pk_bf16_f32 v0, v7, v15
	v_cvt_pk_bf16_f32 v1, v17, v19
	v_cvt_pk_bf16_f32 v2, v21, v55
	v_cvt_pk_bf16_f32 v3, v57, v61
	v_lshl_add_u64 v[4:5], v[58:59], 0, v[10:11]
	global_store_dwordx4 v[4:5], v[0:3], off
	s_waitcnt lgkmcnt(0)
	s_mov_b64 s[24:25], 0

; #define LAS __attribute__((address_space(3)))
; #define LDS_WAIT() asm volatile("s_waitcnt lgkmcnt(0)" ::: "memory")
; __device__ __forceinline__ void p0_transpose_item(const float* W, int K, int N, bfu* WT, int drow0, LAS float* scr, int k0, int n0, int lane, const float* gk) {
; #pragma unroll 8
;     for (int i = 0; i < 32; ++i) { const int kk = 2 * i + (lane >> 5); scr[kk * 33 + (lane & 31)] = __builtin_nontemporal_load(W + (size_t)(k0 + kk) * N + n0 + (lane & 31)); }
;     LDS_WAIT(); asm volatile("" ::: "memory");
;     const int c = lane & 7;
;     f32x4 ga = (f32x4){1.f, 1.f, 1.f, 1.f}, gb = ga;
;     if (gk) { ga = *(const f32x4*)(gk + k0 + 8 * c); gb = *(const f32x4*)(gk + k0 + 8 * c + 4); }
.LBB0_32:
	v_lshl_add_u64 v[54:55], v[20:21], 0, s[28:29]
	v_lshl_add_u64 v[56:57], v[18:19], 0, s[28:29]
	v_lshl_add_u64 v[58:59], v[16:17], 0, s[28:29]
	v_lshl_add_u64 v[60:61], v[14:15], 0, s[28:29]
	v_lshl_add_u64 v[62:63], v[6:7], 0, s[28:29]
	v_lshl_add_u64 v[64:65], v[4:5], 0, s[28:29]
	v_lshl_add_u64 v[66:67], v[2:3], 0, s[28:29]
	v_lshl_add_u64 v[68:69], v[0:1], 0, s[28:29]
	global_load_dword v70, v[54:55], off
	global_load_dword v71, v[56:57], off
	global_load_dword v72, v[58:59], off
	global_load_dword v73, v[60:61], off
	global_load_dword v74, v[62:63], off
	global_load_dword v75, v[64:65], off
	global_load_dword v76, v[66:67], off
	global_load_dword v77, v[68:69], off
	s_add_u32 s28, s28, 0x58000
	s_addc_u32 s29, s29, 0
	v_lshl_add_u64 v[54:55], v[20:21], 0, s[28:29]
	v_lshl_add_u64 v[56:57], v[18:19], 0, s[28:29]
	v_lshl_add_u64 v[58:59], v[16:17], 0, s[28:29]
	v_lshl_add_u64 v[60:61], v[14:15], 0, s[28:29]
	v_lshl_add_u64 v[62:63], v[6:7], 0, s[28:29]
	v_lshl_add_u64 v[64:65], v[4:5], 0, s[28:29]
	v_lshl_add_u64 v[66:67], v[2:3], 0, s[28:29]
	v_lshl_add_u64 v[68:69], v[0:1], 0, s[28:29]
	global_load_dword v78, v[54:55], off
	global_load_dword v79, v[56:57], off
	global_load_dword v80, v[58:59], off
	global_load_dword v81, v[60:61], off
	global_load_dword v82, v[62:63], off
	global_load_dword v83, v[64:65], off
	global_load_dword v84, v[66:67], off
	global_load_dword v85, v[68:69], off
	s_add_u32 s28, s28, 0x58000
	s_addc_u32 s29, s29, 0
	v_lshl_add_u64 v[54:55], v[20:21], 0, s[28:29]
	v_lshl_add_u64 v[56:57], v[18:19], 0, s[28:29]
	v_lshl_add_u64 v[58:59], v[16:17], 0, s[28:29]
	v_lshl_add_u64 v[60:61], v[14:15], 0, s[28:29]
	v_lshl_add_u64 v[62:63], v[6:7], 0, s[28:29]
	v_lshl_add_u64 v[64:65], v[4:5], 0, s[28:29]
	v_lshl_add_u64 v[66:67], v[2:3], 0, s[28:29]
	v_lshl_add_u64 v[68:69], v[0:1], 0, s[28:29]
	global_load_dword v86, v[54:55], off
	global_load_dword v87, v[56:57], off
	global_load_dword v88, v[58:59], off
	global_load_dword v89, v[60:61], off
	global_load_dword v90, v[62:63], off
	global_load_dword v91, v[64:65], off
	global_load_dword v92, v[66:67], off
	global_load_dword v93, v[68:69], off
	s_add_u32 s28, s28, 0x58000
	s_addc_u32 s29, s29, 0
	v_lshl_add_u64 v[54:55], v[20:21], 0, s[28:29]
	v_lshl_add_u64 v[56:57], v[18:19], 0, s[28:29]
	v_lshl_add_u64 v[58:59], v[16:17], 0, s[28:29]
	v_lshl_add_u64 v[60:61], v[14:15], 0, s[28:29]
	v_lshl_add_u64 v[62:63], v[6:7], 0, s[28:29]
	v_lshl_add_u64 v[64:65], v[4:5], 0, s[28:29]
	v_lshl_add_u64 v[66:67], v[2:3], 0, s[28:29]
	v_lshl_add_u64 v[68:69], v[0:1], 0, s[28:29]
	global_load_dword v94, v[54:55], off
	global_load_dword v95, v[56:57], off
	global_load_dword v96, v[58:59], off
	global_load_dword v97, v[60:61], off
	global_load_dword v98, v[62:63], off
	global_load_dword v99, v[64:65], off
	global_load_dword v100, v[66:67], off
	global_load_dword v101, v[68:69], off
	s_add_u32 s28, s28, 0x58000
	s_addc_u32 s29, s29, 0
	v_add_u32_e32 v54, 0x400, v10
	s_waitcnt vmcnt(30)
	ds_write2_b32 v10, v70, v71 offset1:66
	s_waitcnt vmcnt(28)
	ds_write2_b32 v10, v72, v73 offset0:132 offset1:198
	s_waitcnt vmcnt(26)
	ds_write2_b32 v54, v74, v75 offset0:8 offset1:74
	s_waitcnt vmcnt(24)
	ds_write2_b32 v54, v76, v77 offset0:140 offset1:206
	v_add_u32_e32 v10, 0x840, v10
	v_add_u32_e32 v54, 0x400, v10
	s_waitcnt vmcnt(22)
	ds_write2_b32 v10, v78, v79 offset1:66
	s_waitcnt vmcnt(20)
	ds_write2_b32 v10, v80, v81 offset0:132 offset1:198
	s_waitcnt vmcnt(18)
	ds_write2_b32 v54, v82, v83 offset0:8 offset1:74
	s_waitcnt vmcnt(16)
	ds_write2_b32 v54, v84, v85 offset0:140 offset1:206
	v_add_u32_e32 v10, 0x840, v10
	v_add_u32_e32 v54, 0x400, v10
	s_waitcnt vmcnt(14)
	ds_write2_b32 v10, v86, v87 offset1:66
	s_waitcnt vmcnt(12)
	ds_write2_b32 v10, v88, v89 offset0:132 offset1:198
	s_waitcnt vmcnt(10)
	ds_write2_b32 v54, v90, v91 offset0:8 offset1:74
	s_waitcnt vmcnt(8)
	ds_write2_b32 v54, v92, v93 offset0:140 offset1:206
	v_add_u32_e32 v10, 0x840, v10
	v_add_u32_e32 v54, 0x400, v10
	s_waitcnt vmcnt(6)
	ds_write2_b32 v10, v94, v95 offset1:66
	s_waitcnt vmcnt(4)
	ds_write2_b32 v10, v96, v97 offset0:132 offset1:198
	s_waitcnt vmcnt(2)
	ds_write2_b32 v54, v98, v99 offset0:8 offset1:74
	s_waitcnt vmcnt(0)
	ds_write2_b32 v54, v100, v101 offset0:140 offset1:206
	v_add_u32_e32 v10, 0x840, v10
	s_waitcnt lgkmcnt(0)
	s_and_b32 s28, s39, 0xffff
	s_waitcnt lgkmcnt(0)
	s_cmp_lg_u64 s[26:27], 0
	s_cbranch_scc0 .LBB0_58
	s_lshl_b32 s40, s22, 11
	s_ashr_i32 s41, s40, 31
	s_lshl_b64 s[40:41], s[40:41], 2
	s_add_u32 s26, s26, s40
	s_addc_u32 s27, s27, s41
	s_lshl_b32 s29, s28, 2
	s_add_u32 s26, s26, s29
	s_addc_u32 s27, s27, 0
	v_lshlrev_b32_e32 v10, 2, v8
	global_load_dwordx4 v[0:3], v10, s[26:27] offset:16
	global_load_dwordx4 v[4:7], v10, s[26:27]
	s_cbranch_execnz .LBB0_36

; #define LAS __attribute__((address_space(3)))
; #define LDS_WAIT() asm volatile("s_waitcnt lgkmcnt(0)" ::: "memory")
; __device__ __forceinline__ unsigned pk2(float lo, float hi) { return pg8::cvt_pk_bf16(lo, hi); }
; __device__ __forceinline__ void p0_transpose_item(const float* W, int K, int N, bfu* WT, int drow0, LAS float* scr, int k0, int n0, int lane, const float* gk) {
; #pragma unroll 8
;     for (int i = 0; i < 32; ++i) { const int kk = 2 * i + (lane >> 5); scr[kk * 33 + (lane & 31)] = __builtin_nontemporal_load(W + (size_t)(k0 + kk) * N + n0 + (lane & 31)); }
;     LDS_WAIT(); asm volatile("" ::: "memory");
;     const int c = lane & 7;
;     f32x4 ga = (f32x4){1.f, 1.f, 1.f, 1.f}, gb = ga;
;     if (gk) { ga = *(const f32x4*)(gk + k0 + 8 * c); gb = *(const f32x4*)(gk + k0 + 8 * c + 4); }
; #pragma unroll
;     for (int j = 0; j < 4; ++j) { const int n = (lane >> 3) + 8 * j; const LAS float* s = scr + (8 * c) * 33 + n;
;         v4u o; o.x = pk2(s[0 * 33] * ga.x, s[1 * 33] * ga.y); o.y = pk2(s[2 * 33] * ga.z, s[3 * 33] * ga.w); o.z = pk2(s[4 * 33] * gb.x, s[5 * 33] * gb.y); o.w = pk2(s[6 * 33] * gb.z, s[7 * 33] * gb.w);
;         *(v4u*)(WT + (size_t)(drow0 + n) * K + k0 + 8 * c) = o; }
;     LDS_WAIT(); asm volatile("" ::: "memory");
.LBB0_48:
	v_lshl_add_u64 v[54:55], v[20:21], 0, s[26:27]
	v_lshl_add_u64 v[56:57], v[18:19], 0, s[26:27]
	v_lshl_add_u64 v[58:59], v[16:17], 0, s[26:27]
	v_lshl_add_u64 v[60:61], v[14:15], 0, s[26:27]
	v_lshl_add_u64 v[62:63], v[6:7], 0, s[26:27]
	v_lshl_add_u64 v[64:65], v[4:5], 0, s[26:27]
	v_lshl_add_u64 v[66:67], v[2:3], 0, s[26:27]
	v_lshl_add_u64 v[68:69], v[0:1], 0, s[26:27]
	global_load_dword v70, v[54:55], off
	global_load_dword v71, v[56:57], off
	global_load_dword v72, v[58:59], off
	global_load_dword v73, v[60:61], off
	global_load_dword v74, v[62:63], off
	global_load_dword v75, v[64:65], off
	global_load_dword v76, v[66:67], off
	global_load_dword v77, v[68:69], off
	s_add_u32 s26, s26, 0x20000
	s_addc_u32 s27, s27, 0
	v_lshl_add_u64 v[54:55], v[20:21], 0, s[26:27]
	v_lshl_add_u64 v[56:57], v[18:19], 0, s[26:27]
	v_lshl_add_u64 v[58:59], v[16:17], 0, s[26:27]
	v_lshl_add_u64 v[60:61], v[14:15], 0, s[26:27]
	v_lshl_add_u64 v[62:63], v[6:7], 0, s[26:27]
	v_lshl_add_u64 v[64:65], v[4:5], 0, s[26:27]
	v_lshl_add_u64 v[66:67], v[2:3], 0, s[26:27]
	v_lshl_add_u64 v[68:69], v[0:1], 0, s[26:27]
	global_load_dword v78, v[54:55], off
	global_load_dword v79, v[56:57], off
	global_load_dword v80, v[58:59], off
	global_load_dword v81, v[60:61], off
	global_load_dword v82, v[62:63], off
	global_load_dword v83, v[64:65], off
	global_load_dword v84, v[66:67], off
	global_load_dword v85, v[68:69], off
	s_add_u32 s26, s26, 0x20000
	s_addc_u32 s27, s27, 0
	v_lshl_add_u64 v[54:55], v[20:21], 0, s[26:27]
	v_lshl_add_u64 v[56:57], v[18:19], 0, s[26:27]
	v_lshl_add_u64 v[58:59], v[16:17], 0, s[26:27]
	v_lshl_add_u64 v[60:61], v[14:15], 0, s[26:27]
	v_lshl_add_u64 v[62:63], v[6:7], 0, s[26:27]
	v_lshl_add_u64 v[64:65], v[4:5], 0, s[26:27]
	v_lshl_add_u64 v[66:67], v[2:3], 0, s[26:27]
	v_lshl_add_u64 v[68:69], v[0:1], 0, s[26:27]
	global_load_dword v86, v[54:55], off
	global_load_dword v87, v[56:57], off
	global_load_dword v88, v[58:59], off
	global_load_dword v89, v[60:61], off
	global_load_dword v90, v[62:63], off
	global_load_dword v91, v[64:65], off
	global_load_dword v92, v[66:67], off
	global_load_dword v93, v[68:69], off
	s_add_u32 s26, s26, 0x20000
	s_addc_u32 s27, s27, 0
	v_lshl_add_u64 v[54:55], v[20:21], 0, s[26:27]
	v_lshl_add_u64 v[56:57], v[18:19], 0, s[26:27]
	v_lshl_add_u64 v[58:59], v[16:17], 0, s[26:27]
	v_lshl_add_u64 v[60:61], v[14:15], 0, s[26:27]
	v_lshl_add_u64 v[62:63], v[6:7], 0, s[26:27]
	v_lshl_add_u64 v[64:65], v[4:5], 0, s[26:27]
	v_lshl_add_u64 v[66:67], v[2:3], 0, s[26:27]
	v_lshl_add_u64 v[68:69], v[0:1], 0, s[26:27]
	global_load_dword v94, v[54:55], off
	global_load_dword v95, v[56:57], off
	global_load_dword v96, v[58:59], off
	global_load_dword v97, v[60:61], off
	global_load_dword v98, v[62:63], off
	global_load_dword v99, v[64:65], off
	global_load_dword v100, v[66:67], off
	global_load_dword v101, v[68:69], off
	s_add_u32 s26, s26, 0x20000
	s_addc_u32 s27, s27, 0
	v_add_u32_e32 v54, 0x400, v10
	s_waitcnt vmcnt(30)
	ds_write2_b32 v10, v70, v71 offset1:66
	s_waitcnt vmcnt(28)
	ds_write2_b32 v10, v72, v73 offset0:132 offset1:198
	s_waitcnt vmcnt(26)
	ds_write2_b32 v54, v74, v75 offset0:8 offset1:74
	s_waitcnt vmcnt(24)
	ds_write2_b32 v54, v76, v77 offset0:140 offset1:206
	v_add_u32_e32 v10, 0x840, v10
	v_add_u32_e32 v54, 0x400, v10
	s_waitcnt vmcnt(22)
	ds_write2_b32 v10, v78, v79 offset1:66
	s_waitcnt vmcnt(20)
	ds_write2_b32 v10, v80, v81 offset0:132 offset1:198
	s_waitcnt vmcnt(18)
	ds_write2_b32 v54, v82, v83 offset0:8 offset1:74
	s_waitcnt vmcnt(16)
	ds_write2_b32 v54, v84, v85 offset0:140 offset1:206
	v_add_u32_e32 v10, 0x840, v10
	v_add_u32_e32 v54, 0x400, v10
	s_waitcnt vmcnt(14)
	ds_write2_b32 v10, v86, v87 offset1:66
	s_waitcnt vmcnt(12)
	ds_write2_b32 v10, v88, v89 offset0:132 offset1:198
	s_waitcnt vmcnt(10)
	ds_write2_b32 v54, v90, v91 offset0:8 offset1:74
	s_waitcnt vmcnt(8)
	ds_write2_b32 v54, v92, v93 offset0:140 offset1:206
	v_add_u32_e32 v10, 0x840, v10
	v_add_u32_e32 v54, 0x400, v10
	s_waitcnt vmcnt(6)
	ds_write2_b32 v10, v94, v95 offset1:66
	s_waitcnt vmcnt(4)
	ds_write2_b32 v10, v96, v97 offset0:132 offset1:198
	s_waitcnt vmcnt(2)
	ds_write2_b32 v54, v98, v99 offset0:8 offset1:74
	s_waitcnt vmcnt(0)
	ds_write2_b32 v54, v100, v101 offset0:140 offset1:206
	v_add_u32_e32 v10, 0x840, v10
	s_and_b32 s4, s30, 0x3fc0
	s_lshl_b32 s26, s38, 5
	s_addk_i32 s4, 0xe700
	s_and_b32 s28, s26, 0x7e0
	s_lshl_b64 s[26:27], s[22:23], 23
	s_add_u32 s23, s24, s26
	s_waitcnt lgkmcnt(0)
	s_addc_u32 s26, s25, s27
	s_lshl_b64 s[24:25], s[4:5], 1
	s_add_u32 s24, s23, s24
	ds_read2_b32 v[4:5], v25 offset0:33 offset1:41
	ds_read2_b32 v[6:7], v25 offset1:8
	ds_read2_b32 v[14:15], v25 offset0:66 offset1:74
	ds_read2_b32 v[16:17], v25 offset0:99 offset1:107
	ds_read2_b32 v[18:19], v25 offset0:132 offset1:140
	ds_read2_b32 v[20:21], v25 offset0:165 offset1:173
	ds_read2_b32 v[54:55], v25 offset0:198 offset1:206
	ds_read2_b32 v[56:57], v25 offset0:231 offset1:239
	s_addc_u32 s25, s26, s25
	v_lshlrev_b32_e32 v10, 1, v8
	v_lshl_add_u64 v[0:1], s[24:25], 0, v[10:11]
	v_lshl_add_u64 v[58:59], v[0:1], 0, s[18:19]
	s_waitcnt lgkmcnt(6)
	v_cvt_pk_bf16_f32 v0, v6, v4
	v_or_b32_e32 v4, s28, v24
	v_lshlrev_b32_e32 v10, 12, v4
	s_waitcnt lgkmcnt(4)
	v_cvt_pk_bf16_f32 v1, v14, v16
	s_waitcnt lgkmcnt(2)
	v_cvt_pk_bf16_f32 v2, v18, v20
	s_waitcnt lgkmcnt(0)
	v_cvt_pk_bf16_f32 v3, v54, v56
	v_lshl_add_u64 v[60:61], v[58:59], 0, v[10:11]
	global_store_dwordx4 v[60:61], v[0:3], off
	v_or_b32_e32 v4, s28, v26
	v_lshlrev_b32_e32 v10, 12, v4
	v_cvt_pk_bf16_f32 v0, v7, v5
	v_cvt_pk_bf16_f32 v1, v15, v17
	v_cvt_pk_bf16_f32 v2, v19, v21
	v_cvt_pk_bf16_f32 v3, v55, v57
	ds_read2_b32 v[6:7], v25 offset0:49 offset1:57
	ds_read2_b32 v[14:15], v25 offset0:16 offset1:24
	ds_read2_b32 v[16:17], v25 offset0:82 offset1:90
	ds_read2_b32 v[18:19], v25 offset0:115 offset1:123
	ds_read2_b32 v[20:21], v25 offset0:148 offset1:156
	ds_read2_b32 v[54:55], v25 offset0:181 offset1:189
	ds_read2_b32 v[56:57], v25 offset0:214 offset1:222
	ds_read2_b32 v[60:61], v25 offset0:247 offset1:255
	v_lshl_add_u64 v[4:5], v[58:59], 0, v[10:11]
	global_store_dwordx4 v[4:5], v[0:3], off
	v_or_b32_e32 v4, s28, v27
	v_lshlrev_b32_e32 v10, 12, v4
	s_waitcnt lgkmcnt(6)
	v_cvt_pk_bf16_f32 v0, v14, v6
	s_waitcnt lgkmcnt(4)
	v_cvt_pk_bf16_f32 v1, v16, v18
	s_waitcnt lgkmcnt(2)
	v_cvt_pk_bf16_f32 v2, v20, v54
	s_waitcnt lgkmcnt(0)
	v_cvt_pk_bf16_f32 v3, v56, v60
	v_lshl_add_u64 v[4:5], v[58:59], 0, v[10:11]
	global_store_dwordx4 v[4:5], v[0:3], off
	v_or_b32_e32 v4, s28, v28
	v_lshlrev_b32_e32 v10, 12, v4
	v_cvt_pk_bf16_f32 v0, v15, v7
	v_cvt_pk_bf16_f32 v1, v17, v19
	v_cvt_pk_bf16_f32 v2, v21, v55
	v_cvt_pk_bf16_f32 v3, v57, v61
	v_lshl_add_u64 v[4:5], v[58:59], 0, v[10:11]
	global_store_dwordx4 v[4:5], v[0:3], off
	s_waitcnt lgkmcnt(0)

; #define LDS_WAIT() asm volatile("s_waitcnt lgkmcnt(0)" ::: "memory")
; __device__ __forceinline__ void p0_transpose_item(const float* W, int K, int N, bfu* WT, int drow0, LAS float* scr, int k0, int n0, int lane, const float* gk) {
;     ...
;     for (int i = 0; i < 32; ++i) { const int kk = 2 * i + (lane >> 5); scr[kk * 33 + (lane & 31)] = __builtin_nontemporal_load(W + (size_t)(k0 + kk) * N + n0 + (lane & 31)); }
;     LDS_WAIT(); asm volatile("" ::: "memory");
;     const int c = lane & 7;
;     f32x4 ga = (f32x4){1.f, 1.f, 1.f, 1.f}, gb = ga;
;     if (gk) { ga = *(const f32x4*)(gk + k0 + 8 * c); gb = *(const f32x4*)(gk + k0 + 8 * c + 4); }
.LBB0_53:
	v_lshl_add_u64 v[54:55], v[20:21], 0, s[34:35]
	v_lshl_add_u64 v[56:57], v[18:19], 0, s[34:35]
	v_lshl_add_u64 v[58:59], v[16:17], 0, s[34:35]
	v_lshl_add_u64 v[60:61], v[14:15], 0, s[34:35]
	v_lshl_add_u64 v[62:63], v[6:7], 0, s[34:35]
	v_lshl_add_u64 v[64:65], v[4:5], 0, s[34:35]
	v_lshl_add_u64 v[66:67], v[2:3], 0, s[34:35]
	v_lshl_add_u64 v[68:69], v[0:1], 0, s[34:35]
	global_load_dword v70, v[54:55], off
	global_load_dword v71, v[56:57], off
	global_load_dword v72, v[58:59], off
	global_load_dword v73, v[60:61], off
	global_load_dword v74, v[62:63], off
	global_load_dword v75, v[64:65], off
	global_load_dword v76, v[66:67], off
	global_load_dword v77, v[68:69], off
	s_add_u32 s34, s34, 0x64000
	s_addc_u32 s35, s35, 0
	v_lshl_add_u64 v[54:55], v[20:21], 0, s[34:35]
	v_lshl_add_u64 v[56:57], v[18:19], 0, s[34:35]
	v_lshl_add_u64 v[58:59], v[16:17], 0, s[34:35]
	v_lshl_add_u64 v[60:61], v[14:15], 0, s[34:35]
	v_lshl_add_u64 v[62:63], v[6:7], 0, s[34:35]
	v_lshl_add_u64 v[64:65], v[4:5], 0, s[34:35]
	v_lshl_add_u64 v[66:67], v[2:3], 0, s[34:35]
	v_lshl_add_u64 v[68:69], v[0:1], 0, s[34:35]
	global_load_dword v78, v[54:55], off
	global_load_dword v79, v[56:57], off
	global_load_dword v80, v[58:59], off
	global_load_dword v81, v[60:61], off
	global_load_dword v82, v[62:63], off
	global_load_dword v83, v[64:65], off
	global_load_dword v84, v[66:67], off
	global_load_dword v85, v[68:69], off
	s_add_u32 s34, s34, 0x64000
	s_addc_u32 s35, s35, 0
	v_lshl_add_u64 v[54:55], v[20:21], 0, s[34:35]
	v_lshl_add_u64 v[56:57], v[18:19], 0, s[34:35]
	v_lshl_add_u64 v[58:59], v[16:17], 0, s[34:35]
	v_lshl_add_u64 v[60:61], v[14:15], 0, s[34:35]
	v_lshl_add_u64 v[62:63], v[6:7], 0, s[34:35]
	v_lshl_add_u64 v[64:65], v[4:5], 0, s[34:35]
	v_lshl_add_u64 v[66:67], v[2:3], 0, s[34:35]
	v_lshl_add_u64 v[68:69], v[0:1], 0, s[34:35]
	global_load_dword v86, v[54:55], off
	global_load_dword v87, v[56:57], off
	global_load_dword v88, v[58:59], off
	global_load_dword v89, v[60:61], off
	global_load_dword v90, v[62:63], off
	global_load_dword v91, v[64:65], off
	global_load_dword v92, v[66:67], off
	global_load_dword v93, v[68:69], off
	s_add_u32 s34, s34, 0x64000
	s_addc_u32 s35, s35, 0
	v_lshl_add_u64 v[54:55], v[20:21], 0, s[34:35]
	v_lshl_add_u64 v[56:57], v[18:19], 0, s[34:35]
	v_lshl_add_u64 v[58:59], v[16:17], 0, s[34:35]
	v_lshl_add_u64 v[60:61], v[14:15], 0, s[34:35]
	v_lshl_add_u64 v[62:63], v[6:7], 0, s[34:35]
	v_lshl_add_u64 v[64:65], v[4:5], 0, s[34:35]
	v_lshl_add_u64 v[66:67], v[2:3], 0, s[34:35]
	v_lshl_add_u64 v[68:69], v[0:1], 0, s[34:35]
	global_load_dword v94, v[54:55], off
	global_load_dword v95, v[56:57], off
	global_load_dword v96, v[58:59], off
	global_load_dword v97, v[60:61], off
	global_load_dword v98, v[62:63], off
	global_load_dword v99, v[64:65], off
	global_load_dword v100, v[66:67], off
	global_load_dword v101, v[68:69], off
	s_add_u32 s34, s34, 0x64000
	s_addc_u32 s35, s35, 0
	v_add_u32_e32 v54, 0x400, v10
	s_waitcnt vmcnt(30)
	ds_write2_b32 v10, v70, v71 offset1:66
	s_waitcnt vmcnt(28)
	ds_write2_b32 v10, v72, v73 offset0:132 offset1:198
	s_waitcnt vmcnt(26)
	ds_write2_b32 v54, v74, v75 offset0:8 offset1:74
	s_waitcnt vmcnt(24)
	ds_write2_b32 v54, v76, v77 offset0:140 offset1:206
	v_add_u32_e32 v10, 0x840, v10
	v_add_u32_e32 v54, 0x400, v10
	s_waitcnt vmcnt(22)
	ds_write2_b32 v10, v78, v79 offset1:66
	s_waitcnt vmcnt(20)
	ds_write2_b32 v10, v80, v81 offset0:132 offset1:198
	s_waitcnt vmcnt(18)
	ds_write2_b32 v54, v82, v83 offset0:8 offset1:74
	s_waitcnt vmcnt(16)
	ds_write2_b32 v54, v84, v85 offset0:140 offset1:206
	v_add_u32_e32 v10, 0x840, v10
	v_add_u32_e32 v54, 0x400, v10
	s_waitcnt vmcnt(14)
	ds_write2_b32 v10, v86, v87 offset1:66
	s_waitcnt vmcnt(12)
	ds_write2_b32 v10, v88, v89 offset0:132 offset1:198
	s_waitcnt vmcnt(10)
	ds_write2_b32 v54, v90, v91 offset0:8 offset1:74
	s_waitcnt vmcnt(8)
	ds_write2_b32 v54, v92, v93 offset0:140 offset1:206
	v_add_u32_e32 v10, 0x840, v10
	v_add_u32_e32 v54, 0x400, v10
	s_waitcnt vmcnt(6)
	ds_write2_b32 v10, v94, v95 offset1:66
	s_waitcnt vmcnt(4)
	ds_write2_b32 v10, v96, v97 offset0:132 offset1:198
	s_waitcnt vmcnt(2)
	ds_write2_b32 v54, v98, v99 offset0:8 offset1:74
	s_waitcnt vmcnt(0)
	ds_write2_b32 v54, v100, v101 offset0:140 offset1:206
	v_add_u32_e32 v10, 0x840, v10
	s_waitcnt lgkmcnt(0)
	s_waitcnt lgkmcnt(0)
	s_cmp_lg_u64 s[30:31], 0
	s_cbranch_scc0 .LBB0_56
	s_lshl_b32 s34, s22, 11
	s_ashr_i32 s35, s34, 31
	s_lshl_b64 s[34:35], s[34:35], 2
	s_add_u32 s4, s30, s34
	s_addc_u32 s23, s31, s35
	s_ashr_i32 s29, s28, 31
	s_lshl_b64 s[30:31], s[28:29], 2
	s_add_u32 s30, s4, s30
	s_addc_u32 s31, s23, s31
	v_lshlrev_b32_e32 v10, 2, v8
	global_load_dwordx4 v[0:3], v10, s[30:31] offset:16
	global_load_dwordx4 v[4:7], v10, s[30:31]
	s_cbranch_execnz .LBB0_21
	s_branch .LBB0_20

; __device__ __forceinline__ unsigned pk2(float lo, float hi) { return pg8::cvt_pk_bf16(lo, hi); }
; __device__ __forceinline__ void xn_rows(const float* x, bfu* XB, float* RS, int gw, int NGW, int lane) {
;     for (int m = gw; m < M; m += NGW) {
;         const f32x4* xr = (const f32x4*)(x + (size_t)m * DM) + lane; f32x4 v[8]; float s = 0.f;
; #pragma unroll
;         for (int j = 0; j < 8; ++j) { v[j] = __builtin_nontemporal_load(xr + 64 * j); s += (v[j].x * v[j].x + v[j].y * v[j].y) + (v[j].z * v[j].z + v[j].w * v[j].w); }
;         const float rstd = 1.f / sqrtf(wave_sum(s) * (1.f / DM) + EPS);
;         v2u* o8 = (v2u*)(XB + (size_t)m * DM) + lane;
; #pragma unroll
;         for (int j = 0; j < 8; ++j) { v2u w; w.x = pk2(v[j].x, v[j].y); w.y = pk2(v[j].z, v[j].w); o8[64 * j] = w; }
;         if (lane == 0) RS[m] = rstd;
;     }
; }
.LBB0_67:
	s_waitcnt lgkmcnt(0)
	global_load_dwordx4 v[14:17], v[2:3], off offset:-4096
	global_load_dwordx4 v[18:21], v[2:3], off offset:-3072
	global_load_dwordx4 v[22:25], v[2:3], off offset:-2048
	global_load_dwordx4 v[26:29], v[2:3], off offset:-1024
	global_load_dwordx4 v[30:33], v[2:3], off
	global_load_dwordx4 v[34:37], v[2:3], off offset:1024
	global_load_dwordx4 v[38:41], v[2:3], off offset:2048
	global_load_dwordx4 v[42:45], v[2:3], off offset:3072
	s_waitcnt vmcnt(7)
	v_mul_f32_e32 v13, v15, v15
	v_mul_f32_e32 v46, v17, v17
	s_waitcnt vmcnt(6)
	v_mul_f32_e32 v47, v19, v19
	v_mul_f32_e32 v48, v21, v21
	s_waitcnt vmcnt(5)
	v_mul_f32_e32 v49, v23, v23
	v_mul_f32_e32 v50, v25, v25
	v_fmac_f32_e32 v13, v14, v14
	v_fmac_f32_e32 v46, v16, v16
	v_fmac_f32_e32 v47, v18, v18
	v_fmac_f32_e32 v48, v20, v20
	s_waitcnt vmcnt(4)
	v_mul_f32_e32 v51, v27, v27
	v_mul_f32_e32 v52, v29, v29
	v_fmac_f32_e32 v49, v22, v22
	v_fmac_f32_e32 v50, v24, v24
	v_add_f32_e32 v13, v13, v46
	v_add_f32_e32 v46, v47, v48
	s_waitcnt vmcnt(3)
	v_mul_f32_e32 v53, v31, v31
	v_mul_f32_e32 v54, v33, v33
	v_fmac_f32_e32 v51, v26, v26
	v_fmac_f32_e32 v52, v28, v28
	v_add_f32_e32 v47, v49, v50
	v_add_f32_e32 v13, v13, v46
	s_waitcnt vmcnt(2)
	v_mul_f32_e32 v55, v35, v35
	v_mul_f32_e32 v56, v37, v37
	v_fmac_f32_e32 v53, v30, v30
	v_fmac_f32_e32 v54, v32, v32
	v_add_f32_e32 v48, v51, v52
	v_add_f32_e32 v13, v13, v47
	s_waitcnt vmcnt(1)
	v_mul_f32_e32 v57, v39, v39
	v_mul_f32_e32 v58, v41, v41
	v_fmac_f32_e32 v55, v34, v34
	v_fmac_f32_e32 v56, v36, v36
	v_add_f32_e32 v49, v53, v54
	v_add_f32_e32 v13, v13, v48
	s_waitcnt vmcnt(0)
	v_mul_f32_e32 v59, v43, v43
	v_mul_f32_e32 v60, v45, v45
	v_fmac_f32_e32 v57, v38, v38
	v_fmac_f32_e32 v58, v40, v40
	v_add_f32_e32 v50, v55, v56
	v_add_f32_e32 v13, v13, v49
	v_fmac_f32_e32 v59, v42, v42
	v_fmac_f32_e32 v60, v44, v44
	v_add_f32_e32 v51, v57, v58
	v_add_f32_e32 v13, v13, v50
	v_add_f32_e32 v52, v59, v60
	v_add_f32_e32 v13, v13, v51
	v_add_f32_e32 v13, v13, v52
	v_cvt_pk_bf16_f32 v14, v14, v15
	v_cvt_pk_bf16_f32 v15, v16, v17
	v_cvt_pk_bf16_f32 v16, v18, v19
	v_cvt_pk_bf16_f32 v19, v24, v25
	s_waitcnt lgkmcnt(0)
	s_nop 1
	v_add_f32_dpp v13, v13, v13 quad_perm:[1,0,3,2] row_mask:0xf bank_mask:0xf
	v_cvt_pk_bf16_f32 v17, v20, v21
	v_cvt_pk_bf16_f32 v20, v26, v27
	global_store_dwordx2 v[4:5], v[14:15], off
	global_store_dwordx2 v[4:5], v[16:17], off offset:512
	v_cvt_pk_bf16_f32 v18, v22, v23
	s_nop 1
	v_add_f32_dpp v13, v13, v13 quad_perm:[2,3,0,1] row_mask:0xf bank_mask:0xf
	v_cvt_pk_bf16_f32 v26, v38, v39
	v_cvt_pk_bf16_f32 v16, v42, v43
	v_cvt_pk_bf16_f32 v17, v44, v45
	v_cvt_pk_bf16_f32 v21, v28, v29
	s_nop 1
	v_add_f32_dpp v13, v13, v13 row_half_mirror row_mask:0xf bank_mask:0xf
	v_cvt_pk_bf16_f32 v22, v30, v31
	v_cvt_pk_bf16_f32 v23, v32, v33
	v_cvt_pk_bf16_f32 v24, v34, v35
	v_cvt_pk_bf16_f32 v25, v36, v37
	s_nop 1
	v_add_f32_dpp v13, v13, v13 row_mirror row_mask:0xf bank_mask:0xf
	v_cvt_pk_bf16_f32 v27, v40, v41
	global_store_dwordx2 v[4:5], v[18:19], off offset:1024
	global_store_dwordx2 v[4:5], v[20:21], off offset:1536
	global_store_dwordx2 v[4:5], v[22:23], off offset:2048
	global_store_dwordx2 v[4:5], v[24:25], off offset:2560
	global_store_dwordx2 v[4:5], v[26:27], off offset:3072
	global_store_dwordx2 v[4:5], v[16:17], off offset:3584
	v_mov_b32_e32 v14, v13
	s_nop 1
	v_permlane16_swap_b32_e32 v13, v14
	v_add_f32_e32 v13, v13, v14
	v_mov_b32_e32 v14, v13
	s_nop 1
	v_permlane32_swap_b32_e32 v13, v14
	v_add_f32_e32 v13, v13, v14
	s_and_saveexec_b64 s[24:25], s[4:5]
	s_cbranch_execz .LBB0_66
	s_waitcnt lgkmcnt(0)
	v_fmamk_f32 v13, v13, 0x3a000000, v0
	v_mul_f32_e32 v14, 0x4f800000, v13
	v_cmp_gt_f32_e32 vcc, s15, v13
	s_nop 1
	v_cndmask_b32_e32 v13, v13, v14, vcc
	v_sqrt_f32_e32 v14, v13
	s_nop 0
	v_add_u32_e32 v15, -1, v14
	v_fma_f32 v17, -v15, v14, v13
	v_add_u32_e32 v16, 1, v14
	v_cmp_ge_f32_e64 s[6:7], 0, v17
	s_nop 1
	v_cndmask_b32_e64 v15, v14, v15, s[6:7]
	v_fma_f32 v14, -v16, v14, v13
	v_cmp_lt_f32_e64 s[6:7], 0, v14
	s_nop 1
	v_cndmask_b32_e64 v14, v15, v16, s[6:7]
	v_mul_f32_e32 v15, 0x37800000, v14
	v_cndmask_b32_e32 v14, v14, v15, vcc
	v_cmp_class_f32_e32 vcc, v13, v9
	s_nop 1
	v_cndmask_b32_e32 v13, v14, v13, vcc
	v_div_scale_f32 v14, s[6:7], v13, v13, 1.0
	v_rcp_f32_e32 v15, v14
	s_nop 0
	v_fma_f32 v16, -v14, v15, 1.0
	v_fmac_f32_e32 v15, v16, v15
	v_div_scale_f32 v16, vcc, 1.0, v13, 1.0
	v_mul_f32_e32 v17, v16, v15
	v_fma_f32 v18, -v14, v17, v16
	v_fmac_f32_e32 v17, v18, v15
	v_fma_f32 v14, -v14, v17, v16
	v_div_fmas_f32 v14, v14, v15, v17
	v_div_fixup_f32 v13, v14, v13, 1.0
	global_store_dword v1, v13, s[16:17]
	s_branch .LBB0_66
